# strategy 7: EpiResidNorm row-sum lane^16 / lane^32 hops via v_permlane16_swap / v_permlane32_swap on a copy instead of ds_bpermute_b32 round trips (bit-identical sums)
# speedup vs baseline: 1.0025x; 1.0025x over previous
; __device__ __forceinline__ float shx(float v, int m, int lane) { return __int_as_float(__builtin_amdgcn_ds_bpermute((lane ^ m) << 2, __float_as_int(v))); }
;     __device__ __forceinline__ void operator()(const f32x4 (&acc)[2][2][4][2], const Unit& u, int wr, int wc, int fr, int fq) const {
;     ...
;         f32x4 gv[2][2];
; #pragma unroll
;         for (int bj = 0; bj < 2; ++bj)
; #pragma unroll
;             for (int n = 0; n < 2; ++n) gv[bj][n] = *(const f32x4*)(gate + b * 9216 + col0 + bj * HALF + 4 * n) * coef;
;         h16x8 ov[2][4][2];
; #pragma unroll
;         for (int ai = 0; ai < 2; ++ai)
; #pragma unroll
;             for (int m = 0; m < 4; ++m) {
;                 float sq = 0.f;
; #pragma unroll
;                 for (int bj = 0; bj < 2; ++bj) {
;                     const unsigned off = (unsigned)(row0 + ai * HALF + m * 16) * DM + col0 + bj * HALF;
;                     f32x4 xa, xb;
;                     if (F32IN) { xa = *(const f32x4*)(in32 + off); xb = *(const f32x4*)(in32 + off + 4); }
;                     else { const h16x8 xv = *(const h16x8*)(in16 + off); xa = (f32x4){(float)xv[0], (float)xv[1], (float)xv[2], (float)xv[3]}; xb = (f32x4){(float)xv[4], (float)xv[5], (float)xv[6], (float)xv[7]}; }
;                     h16x8 o;
; #pragma unroll
;                     for (int j = 0; j < 4; ++j) { o[j] = (h16)(xa[j] + gv[bj][0][j] * acc[ai][bj][m][0][j]); o[4 + j] = (h16)(xb[j] + gv[bj][1][j] * acc[ai][bj][m][1][j]); }
;                     if (!FINAL) *(h16x8*)(out + off) = o;
;                     ov[ai][m][bj] = o;
; #pragma unroll
;                     for (int j = 0; j < 8; ++j) sq += (float)o[j] * (float)o[j];
;                 }
;                 sq += shx(sq, 16, lane); sq += shx(sq, 32, lane);
;                 if (fq == 0) red[(ai * HALF + wr * 64 + m * 16 + fr) * 4 + wc] = sq;
;             }
.LBB0_567:
	s_lshl_b32 s24, s24, 8
	v_or_b32_e32 v150, s24, v179
	s_lshr_b32 s26, s73, 4
	v_lshl_add_u32 v148, s73, 18, v191
	v_add_u32_e32 v32, v148, v150
	s_nop 0
	s_mulk_i32 s26, 0x2400
	v_lshlrev_b64 v[160:161], 1, v[32:33]
	v_readlane_b32 s48, v253, 12
	v_readlane_b32 s49, v253, 13
	s_ashr_i32 s27, s26, 31
	s_lshl_b64 s[26:27], s[26:27], 2
	v_lshl_add_u64 v[176:177], s[48:49], 0, v[160:161]
	s_add_u32 s28, s94, s26
	s_addc_u32 s29, s95, s27
	v_ashrrev_i32_e32 v151, 31, v150
	v_lshl_add_u64 v[162:163], v[150:151], 2, s[28:29]
	global_load_dwordx4 v[156:159], v[162:163], off
	global_load_dwordx4 v[168:171], v[162:163], off offset:16
	v_mov_b32_e32 v139, v138
	v_lshl_add_u64 v[196:197], s[18:19], 0, v[160:161]
	global_load_dwordx4 v[172:175], v[162:163], off offset:512
	global_load_dwordx4 v[208:211], v[162:163], off offset:528
	v_lshlrev_b32_e32 v251, 1, v32
	v_add_u32_e32 v250, 0x0, v251
	global_load_dwordx4 v[218:221], v250, s[48:49]
	global_load_dwordx4 v[222:225], v250, s[48:49] offset:256
	v_add_u32_e32 v250, 0x8000, v251
	global_load_dwordx4 v[226:229], v250, s[48:49]
	global_load_dwordx4 v[230:233], v250, s[48:49] offset:256
	v_add_u32_e32 v250, 0x10000, v251
	global_load_dwordx4 v[234:237], v250, s[48:49]
	global_load_dwordx4 v[238:241], v250, s[48:49] offset:256
	v_add_u32_e32 v250, 0x18000, v251
	global_load_dwordx4 v[242:245], v250, s[48:49]
	global_load_dwordx4 v[246:249], v250, s[48:49] offset:256
	s_nop 7
	s_nop 4
	s_waitcnt vmcnt(7)
	v_cvt_f32_f16_e32 v198, v218
	v_cvt_f32_f16_sdwa v199, v218 dst_sel:DWORD dst_unused:UNUSED_PAD src0_sel:WORD_1
	v_cvt_f32_f16_e32 v152, v219
	v_cvt_f32_f16_sdwa v153, v219 dst_sel:DWORD dst_unused:UNUSED_PAD src0_sel:WORD_1
	v_cvt_f32_f16_e32 v212, v220
	v_cvt_f32_f16_sdwa v213, v220 dst_sel:DWORD dst_unused:UNUSED_PAD src0_sel:WORD_1
	v_cvt_f32_f16_e32 v154, v221
	v_cvt_f32_f16_sdwa v155, v221 dst_sel:DWORD dst_unused:UNUSED_PAD src0_sel:WORD_1
	s_waitcnt lgkmcnt(0)
	v_pk_mul_f32 v[164:165], v[158:159], v[138:139]
	v_pk_mul_f32 v[166:167], v[156:157], v[142:143]
	v_pk_mul_f32 v[160:161], v[138:139], v[170:171]
	v_pk_mul_f32 v[162:163], v[142:143], v[168:169]
	v_pk_fma_f32 v[126:127], v[126:127], v[166:167], v[198:199]
	v_pk_fma_f32 v[128:129], v[128:129], v[164:165], v[152:153]
	v_pk_fma_f32 v[122:123], v[122:123], v[162:163], v[212:213]
	v_pk_fma_f32 v[124:125], v[124:125], v[160:161], v[154:155]
	v_cvt_pk_f16_f32 v168, v126, v127
	v_cvt_pk_f16_f32 v169, v128, v129
	v_cvt_pk_f16_f32 v170, v122, v123
	v_cvt_pk_f16_f32 v171, v124, v125
	global_store_dwordx4 v[196:197], v[168:171], off
	v_cvt_f32_f16_e32 v124, v168
	v_cvt_f32_f16_sdwa v125, v168 dst_sel:DWORD dst_unused:UNUSED_PAD src0_sel:WORD_1
	v_cvt_f32_f16_e32 v122, v169
	v_cvt_f32_f16_sdwa v123, v169 dst_sel:DWORD dst_unused:UNUSED_PAD src0_sel:WORD_1
	v_cvt_f32_f16_e32 v128, v170
	v_cvt_f32_f16_sdwa v129, v170 dst_sel:DWORD dst_unused:UNUSED_PAD src0_sel:WORD_1
	v_pk_mul_f32 v[168:169], v[124:125], v[124:125]
	v_pk_mul_f32 v[156:157], v[138:139], v[174:175]
	v_pk_mul_f32 v[152:153], v[138:139], v[210:211]
	v_cvt_f32_f16_e32 v126, v171
	v_cvt_f32_f16_sdwa v127, v171 dst_sel:DWORD dst_unused:UNUSED_PAD src0_sel:WORD_1
	v_pk_mul_f32 v[170:171], v[122:123], v[122:123]
	v_add_f32_e32 v139, v168, v169
	v_add_f32_e32 v139, v170, v139
	v_add_f32_e32 v139, v171, v139
	v_pk_mul_f32 v[158:159], v[142:143], v[172:173]
	v_pk_mul_f32 v[172:173], v[128:129], v[128:129]
	v_pk_mul_f32 v[154:155], v[142:143], v[208:209]
	v_add_f32_e32 v139, v172, v139
	v_add_f32_e32 v139, v173, v139
	v_pk_mul_f32 v[174:175], v[126:127], v[126:127]
	s_waitcnt vmcnt(7)
	v_cvt_f32_f16_e32 v168, v222
	v_cvt_f32_f16_sdwa v169, v222 dst_sel:DWORD dst_unused:UNUSED_PAD src0_sel:WORD_1
	v_cvt_f32_f16_e32 v170, v223
	v_cvt_f32_f16_sdwa v171, v223 dst_sel:DWORD dst_unused:UNUSED_PAD src0_sel:WORD_1
	v_cvt_f32_f16_e32 v176, v225
	v_cvt_f32_f16_sdwa v177, v225 dst_sel:DWORD dst_unused:UNUSED_PAD src0_sel:WORD_1
	v_cvt_f32_f16_e32 v172, v224
	v_cvt_f32_f16_sdwa v173, v224 dst_sel:DWORD dst_unused:UNUSED_PAD src0_sel:WORD_1
	v_readlane_b32 s48, v253, 12
	v_readlane_b32 s49, v253, 13
	s_nop 4
	v_add_u32_e32 v250, 0x40000, v251
	global_load_dwordx4 v[218:221], v250, s[48:49]
	global_load_dwordx4 v[222:225], v250, s[48:49] offset:256
	v_pk_fma_f32 v[118:119], v[118:119], v[158:159], v[168:169]
	v_pk_fma_f32 v[120:121], v[120:121], v[156:157], v[170:171]
	v_cvt_pk_f16_f32 v168, v118, v119
	v_cvt_pk_f16_f32 v169, v120, v121
	v_cvt_f32_f16_e32 v120, v168
	v_cvt_f32_f16_sdwa v121, v168 dst_sel:DWORD dst_unused:UNUSED_PAD src0_sel:WORD_1
	v_pk_fma_f32 v[116:117], v[116:117], v[152:153], v[176:177]
	v_pk_fma_f32 v[114:115], v[114:115], v[154:155], v[172:173]
	v_cvt_pk_f16_f32 v171, v116, v117
	v_cvt_f32_f16_e32 v116, v169
	v_cvt_f32_f16_sdwa v117, v169 dst_sel:DWORD dst_unused:UNUSED_PAD src0_sel:WORD_1
	v_add_f32_e32 v139, v174, v139
	v_cvt_pk_f16_f32 v170, v114, v115
	v_cvt_f32_f16_e32 v118, v170
	v_cvt_f32_f16_sdwa v119, v170 dst_sel:DWORD dst_unused:UNUSED_PAD src0_sel:WORD_1
	v_pk_mul_f32 v[172:173], v[120:121], v[120:121]
	v_add_f32_e32 v139, v175, v139
	v_add_f32_e32 v139, v172, v139
	v_cvt_f32_f16_e32 v114, v171
	v_cvt_f32_f16_sdwa v115, v171 dst_sel:DWORD dst_unused:UNUSED_PAD src0_sel:WORD_1
	v_pk_mul_f32 v[176:177], v[116:117], v[116:117]
	v_add_f32_e32 v139, v173, v139
	v_add_f32_e32 v139, v176, v139
	v_pk_mul_f32 v[198:199], v[118:119], v[118:119]
	v_add_f32_e32 v139, v177, v139
	v_add_f32_e32 v139, v198, v139
	v_pk_mul_f32 v[208:209], v[114:115], v[114:115]
	v_add_f32_e32 v139, v199, v139
	v_add_f32_e32 v139, v208, v139
	v_add_f32_e32 v139, v209, v139
	v_mov_b32_e32 v149, v139
	s_nop 1
	v_permlane16_swap_b32_e32 v149, v139
	global_store_dwordx4 v[196:197], v[168:171], off offset:256
	s_waitcnt lgkmcnt(0)
	v_add_f32_e32 v139, v139, v149
	v_mov_b32_e32 v149, v139
	s_nop 1
	v_permlane32_swap_b32_e32 v149, v139
	s_and_saveexec_b64 s[28:29], s[4:5]
	s_cbranch_execz .LBB0_569
	s_waitcnt lgkmcnt(0)
	v_add_f32_e32 v139, v139, v149
	v_add_u32_e32 v149, s72, v190
	ds_write_b32 v149, v139
; __device__ __forceinline__ float shx(float v, int m, int lane) { return __int_as_float(__builtin_amdgcn_ds_bpermute((lane ^ m) << 2, __float_as_int(v))); }
;     __device__ __forceinline__ void operator()(const f32x4 (&acc)[2][2][4][2], const Unit& u, int wr, int wc, int fr, int fq) const {
;     ...
;         for (int ai = 0; ai < 2; ++ai)
; #pragma unroll
;             for (int m = 0; m < 4; ++m) {
;                 float sq = 0.f;
; #pragma unroll
;                 for (int bj = 0; bj < 2; ++bj) {
;                     const unsigned off = (unsigned)(row0 + ai * HALF + m * 16) * DM + col0 + bj * HALF;
;                     f32x4 xa, xb;
;                     if (F32IN) { xa = *(const f32x4*)(in32 + off); xb = *(const f32x4*)(in32 + off + 4); }
;                     else { const h16x8 xv = *(const h16x8*)(in16 + off); xa = (f32x4){(float)xv[0], (float)xv[1], (float)xv[2], (float)xv[3]}; xb = (f32x4){(float)xv[4], (float)xv[5], (float)xv[6], (float)xv[7]}; }
;                     h16x8 o;
; #pragma unroll
;                     for (int j = 0; j < 4; ++j) { o[j] = (h16)(xa[j] + gv[bj][0][j] * acc[ai][bj][m][0][j]); o[4 + j] = (h16)(xb[j] + gv[bj][1][j] * acc[ai][bj][m][1][j]); }
;                     if (!FINAL) *(h16x8*)(out + off) = o;
;                     ov[ai][m][bj] = o;
; #pragma unroll
;                     for (int j = 0; j < 8; ++j) sq += (float)o[j] * (float)o[j];
;                 }
;                 sq += shx(sq, 16, lane); sq += shx(sq, 32, lane);
;                 if (fq == 0) red[(ai * HALF + wr * 64 + m * 16 + fr) * 4 + wc] = sq;
;             }
.LBB0_569:
	s_or_b64 exec, exec, s[28:29]
	v_add_u32_e32 v168, 0x4000, v32
	v_mov_b32_e32 v169, v33
	s_nop 0
	v_lshlrev_b64 v[172:173], 1, v[168:169]
	v_readlane_b32 s48, v253, 12
	v_readlane_b32 s49, v253, 13
	v_add_u32_e32 v174, 0x4080, v32
	v_mov_b32_e32 v175, v33
	v_lshl_add_u64 v[168:169], s[48:49], 0, v[172:173]
	v_lshlrev_b64 v[176:177], 1, v[174:175]
	v_lshl_add_u64 v[172:173], s[18:19], 0, v[172:173]
	v_lshl_add_u64 v[174:175], s[48:49], 0, v[176:177]
	s_nop 7
	s_nop 4
	s_waitcnt vmcnt(9)
	v_cvt_f32_f16_e32 v196, v226
	v_cvt_f32_f16_sdwa v197, v226 dst_sel:DWORD dst_unused:UNUSED_PAD src0_sel:WORD_1
	v_cvt_f32_f16_e32 v168, v227
	v_cvt_f32_f16_sdwa v169, v227 dst_sel:DWORD dst_unused:UNUSED_PAD src0_sel:WORD_1
	v_cvt_f32_f16_e32 v198, v228
	v_cvt_f32_f16_sdwa v199, v228 dst_sel:DWORD dst_unused:UNUSED_PAD src0_sel:WORD_1
	v_cvt_f32_f16_e32 v170, v229
	v_cvt_f32_f16_sdwa v171, v229 dst_sel:DWORD dst_unused:UNUSED_PAD src0_sel:WORD_1
	v_pk_fma_f32 v[110:111], v[110:111], v[166:167], v[196:197]
	v_pk_fma_f32 v[112:113], v[112:113], v[164:165], v[168:169]
	v_pk_fma_f32 v[106:107], v[106:107], v[162:163], v[198:199]
	v_pk_fma_f32 v[108:109], v[108:109], v[160:161], v[170:171]
	v_cvt_pk_f16_f32 v168, v110, v111
	v_cvt_pk_f16_f32 v169, v112, v113
	v_cvt_pk_f16_f32 v170, v106, v107
	v_cvt_pk_f16_f32 v171, v108, v109
	global_store_dwordx4 v[172:173], v[168:171], off
	v_cvt_f32_f16_e32 v108, v168
	v_cvt_f32_f16_sdwa v109, v168 dst_sel:DWORD dst_unused:UNUSED_PAD src0_sel:WORD_1
	v_cvt_f32_f16_e32 v106, v169
	v_cvt_f32_f16_sdwa v107, v169 dst_sel:DWORD dst_unused:UNUSED_PAD src0_sel:WORD_1
	v_cvt_f32_f16_e32 v112, v170
	v_pk_mul_f32 v[168:169], v[108:109], v[108:109]
	v_cvt_f32_f16_sdwa v113, v170 dst_sel:DWORD dst_unused:UNUSED_PAD src0_sel:WORD_1
	v_cvt_f32_f16_e32 v110, v171
	v_cvt_f32_f16_sdwa v111, v171 dst_sel:DWORD dst_unused:UNUSED_PAD src0_sel:WORD_1
	v_pk_mul_f32 v[170:171], v[106:107], v[106:107]
	v_add_f32_e32 v139, v168, v169
	v_add_f32_e32 v139, v170, v139
	v_add_f32_e32 v139, v171, v139
	v_pk_mul_f32 v[196:197], v[112:113], v[112:113]
	v_pk_mul_f32 v[198:199], v[110:111], v[110:111]
	v_add_f32_e32 v139, v196, v139
	v_add_f32_e32 v139, v197, v139
	v_add_f32_e32 v139, v198, v139
	v_add_f32_e32 v139, v199, v139
	s_waitcnt vmcnt(9)
	v_cvt_f32_f16_e32 v168, v230
	v_cvt_f32_f16_sdwa v169, v230 dst_sel:DWORD dst_unused:UNUSED_PAD src0_sel:WORD_1
	v_cvt_f32_f16_e32 v170, v231
	v_cvt_f32_f16_sdwa v171, v231 dst_sel:DWORD dst_unused:UNUSED_PAD src0_sel:WORD_1
	v_cvt_f32_f16_e32 v172, v232
	v_cvt_f32_f16_sdwa v173, v232 dst_sel:DWORD dst_unused:UNUSED_PAD src0_sel:WORD_1
	v_cvt_f32_f16_e32 v174, v233
	v_cvt_f32_f16_sdwa v175, v233 dst_sel:DWORD dst_unused:UNUSED_PAD src0_sel:WORD_1
	v_readlane_b32 s48, v253, 12
	v_readlane_b32 s49, v253, 13
	s_nop 4
	v_add_u32_e32 v250, 0x48000, v251
	global_load_dwordx4 v[226:229], v250, s[48:49]
	global_load_dwordx4 v[230:233], v250, s[48:49] offset:256
	v_pk_fma_f32 v[102:103], v[102:103], v[158:159], v[168:169]
	v_pk_fma_f32 v[104:105], v[104:105], v[156:157], v[170:171]
	v_cvt_pk_f16_f32 v168, v102, v103
	v_cvt_pk_f16_f32 v169, v104, v105
	v_cvt_f32_f16_e32 v104, v168
	v_cvt_f32_f16_sdwa v105, v168 dst_sel:DWORD dst_unused:UNUSED_PAD src0_sel:WORD_1
	v_pk_fma_f32 v[100:101], v[100:101], v[152:153], v[174:175]
	v_pk_fma_f32 v[98:99], v[98:99], v[154:155], v[172:173]
	v_cvt_pk_f16_f32 v171, v100, v101
	v_cvt_f32_f16_e32 v100, v169
	v_cvt_f32_f16_sdwa v101, v169 dst_sel:DWORD dst_unused:UNUSED_PAD src0_sel:WORD_1
	v_cvt_pk_f16_f32 v170, v98, v99
	v_cvt_f32_f16_e32 v102, v170
	v_cvt_f32_f16_sdwa v103, v170 dst_sel:DWORD dst_unused:UNUSED_PAD src0_sel:WORD_1
	v_pk_mul_f32 v[172:173], v[104:105], v[104:105]
	v_cvt_f32_f16_e32 v98, v171
	v_add_f32_e32 v139, v172, v139
	v_cvt_f32_f16_sdwa v99, v171 dst_sel:DWORD dst_unused:UNUSED_PAD src0_sel:WORD_1
	v_pk_mul_f32 v[174:175], v[100:101], v[100:101]
	v_add_f32_e32 v139, v173, v139
	v_add_f32_e32 v139, v174, v139
	v_pk_mul_f32 v[196:197], v[102:103], v[102:103]
	v_add_f32_e32 v139, v175, v139
	v_add_f32_e32 v139, v196, v139
	v_pk_mul_f32 v[208:209], v[98:99], v[98:99]
	v_add_f32_e32 v139, v197, v139
	v_add_f32_e32 v139, v208, v139
	v_add_f32_e32 v139, v209, v139
	s_waitcnt lgkmcnt(0)
	v_mov_b32_e32 v149, v139
	s_nop 1
	v_permlane16_swap_b32_e32 v149, v139
	v_lshl_add_u64 v[172:173], s[18:19], 0, v[176:177]
	global_store_dwordx4 v[172:173], v[168:171], off
	s_waitcnt lgkmcnt(0)
	v_add_f32_e32 v139, v139, v149
	v_mov_b32_e32 v149, v139
	s_nop 1
	v_permlane32_swap_b32_e32 v149, v139
	s_and_saveexec_b64 s[28:29], s[4:5]
	s_cbranch_execz .LBB0_571
	s_waitcnt lgkmcnt(0)
	v_add_f32_e32 v139, v139, v149
	v_add_u32_e32 v149, s72, v190
	ds_write_b32 v149, v139 offset:256
; __device__ __forceinline__ float shx(float v, int m, int lane) { return __int_as_float(__builtin_amdgcn_ds_bpermute((lane ^ m) << 2, __float_as_int(v))); }
;     __device__ __forceinline__ void operator()(const f32x4 (&acc)[2][2][4][2], const Unit& u, int wr, int wc, int fr, int fq) const {
;     ...
;         for (int ai = 0; ai < 2; ++ai)
; #pragma unroll
;             for (int m = 0; m < 4; ++m) {
;                 float sq = 0.f;
; #pragma unroll
;                 for (int bj = 0; bj < 2; ++bj) {
;                     const unsigned off = (unsigned)(row0 + ai * HALF + m * 16) * DM + col0 + bj * HALF;
;                     f32x4 xa, xb;
;                     if (F32IN) { xa = *(const f32x4*)(in32 + off); xb = *(const f32x4*)(in32 + off + 4); }
;                     else { const h16x8 xv = *(const h16x8*)(in16 + off); xa = (f32x4){(float)xv[0], (float)xv[1], (float)xv[2], (float)xv[3]}; xb = (f32x4){(float)xv[4], (float)xv[5], (float)xv[6], (float)xv[7]}; }
;                     h16x8 o;
; #pragma unroll
;                     for (int j = 0; j < 4; ++j) { o[j] = (h16)(xa[j] + gv[bj][0][j] * acc[ai][bj][m][0][j]); o[4 + j] = (h16)(xb[j] + gv[bj][1][j] * acc[ai][bj][m][1][j]); }
;                     if (!FINAL) *(h16x8*)(out + off) = o;
;                     ov[ai][m][bj] = o;
; #pragma unroll
;                     for (int j = 0; j < 8; ++j) sq += (float)o[j] * (float)o[j];
;                 }
;                 sq += shx(sq, 16, lane); sq += shx(sq, 32, lane);
;                 if (fq == 0) red[(ai * HALF + wr * 64 + m * 16 + fr) * 4 + wc] = sq;
;             }
.LBB0_571:
	s_or_b64 exec, exec, s[28:29]
	v_add_u32_e32 v168, 0x8000, v32
	v_mov_b32_e32 v169, v33
	s_nop 0
	v_lshlrev_b64 v[172:173], 1, v[168:169]
	v_readlane_b32 s48, v253, 12
	v_readlane_b32 s49, v253, 13
	v_add_u32_e32 v174, 0x8080, v32
	v_mov_b32_e32 v175, v33
	v_lshl_add_u64 v[168:169], s[48:49], 0, v[172:173]
	v_lshlrev_b64 v[176:177], 1, v[174:175]
	v_lshl_add_u64 v[172:173], s[18:19], 0, v[172:173]
	v_lshl_add_u64 v[174:175], s[48:49], 0, v[176:177]
	s_nop 7
	s_nop 4
	s_waitcnt vmcnt(11)
	v_cvt_f32_f16_e32 v196, v234
	v_cvt_f32_f16_sdwa v197, v234 dst_sel:DWORD dst_unused:UNUSED_PAD src0_sel:WORD_1
	v_cvt_f32_f16_e32 v168, v235
	v_cvt_f32_f16_sdwa v169, v235 dst_sel:DWORD dst_unused:UNUSED_PAD src0_sel:WORD_1
	v_cvt_f32_f16_e32 v198, v236
	v_cvt_f32_f16_sdwa v199, v236 dst_sel:DWORD dst_unused:UNUSED_PAD src0_sel:WORD_1
	v_cvt_f32_f16_e32 v170, v237
	v_cvt_f32_f16_sdwa v171, v237 dst_sel:DWORD dst_unused:UNUSED_PAD src0_sel:WORD_1
	v_pk_fma_f32 v[94:95], v[94:95], v[166:167], v[196:197]
	v_pk_fma_f32 v[96:97], v[96:97], v[164:165], v[168:169]
	v_pk_fma_f32 v[90:91], v[90:91], v[162:163], v[198:199]
	v_pk_fma_f32 v[92:93], v[92:93], v[160:161], v[170:171]
	v_cvt_pk_f16_f32 v168, v94, v95
	v_cvt_pk_f16_f32 v169, v96, v97
	v_cvt_pk_f16_f32 v170, v90, v91
	v_cvt_pk_f16_f32 v171, v92, v93
	global_store_dwordx4 v[172:173], v[168:171], off
	v_cvt_f32_f16_e32 v92, v168
	v_cvt_f32_f16_sdwa v93, v168 dst_sel:DWORD dst_unused:UNUSED_PAD src0_sel:WORD_1
	v_cvt_f32_f16_e32 v90, v169
	v_cvt_f32_f16_sdwa v91, v169 dst_sel:DWORD dst_unused:UNUSED_PAD src0_sel:WORD_1
	v_cvt_f32_f16_e32 v96, v170
	v_pk_mul_f32 v[168:169], v[92:93], v[92:93]
	v_cvt_f32_f16_sdwa v97, v170 dst_sel:DWORD dst_unused:UNUSED_PAD src0_sel:WORD_1
	v_cvt_f32_f16_e32 v94, v171
	v_cvt_f32_f16_sdwa v95, v171 dst_sel:DWORD dst_unused:UNUSED_PAD src0_sel:WORD_1
	v_pk_mul_f32 v[170:171], v[90:91], v[90:91]
	v_add_f32_e32 v139, v168, v169
	v_add_f32_e32 v139, v170, v139
	v_add_f32_e32 v139, v171, v139
	v_pk_mul_f32 v[196:197], v[96:97], v[96:97]
	v_pk_mul_f32 v[198:199], v[94:95], v[94:95]
	v_add_f32_e32 v139, v196, v139
	v_add_f32_e32 v139, v197, v139
	v_add_f32_e32 v139, v198, v139
	v_add_f32_e32 v139, v199, v139
	s_waitcnt vmcnt(11)
	v_cvt_f32_f16_e32 v168, v238
	v_cvt_f32_f16_sdwa v169, v238 dst_sel:DWORD dst_unused:UNUSED_PAD src0_sel:WORD_1
	v_cvt_f32_f16_e32 v170, v239
	v_cvt_f32_f16_sdwa v171, v239 dst_sel:DWORD dst_unused:UNUSED_PAD src0_sel:WORD_1
	v_cvt_f32_f16_e32 v172, v240
	v_cvt_f32_f16_sdwa v173, v240 dst_sel:DWORD dst_unused:UNUSED_PAD src0_sel:WORD_1
	v_cvt_f32_f16_e32 v174, v241
	v_cvt_f32_f16_sdwa v175, v241 dst_sel:DWORD dst_unused:UNUSED_PAD src0_sel:WORD_1
	v_readlane_b32 s48, v253, 12
	v_readlane_b32 s49, v253, 13
	s_nop 4
	v_add_u32_e32 v250, 0x50000, v251
	global_load_dwordx4 v[234:237], v250, s[48:49]
	global_load_dwordx4 v[238:241], v250, s[48:49] offset:256
	v_pk_fma_f32 v[86:87], v[86:87], v[158:159], v[168:169]
	v_pk_fma_f32 v[88:89], v[88:89], v[156:157], v[170:171]
	v_cvt_pk_f16_f32 v168, v86, v87
	v_cvt_pk_f16_f32 v169, v88, v89
	v_cvt_f32_f16_e32 v88, v168
	v_cvt_f32_f16_sdwa v89, v168 dst_sel:DWORD dst_unused:UNUSED_PAD src0_sel:WORD_1
	v_pk_fma_f32 v[84:85], v[84:85], v[152:153], v[174:175]
	v_pk_fma_f32 v[82:83], v[82:83], v[154:155], v[172:173]
	v_cvt_pk_f16_f32 v171, v84, v85
	v_cvt_f32_f16_e32 v84, v169
	v_cvt_f32_f16_sdwa v85, v169 dst_sel:DWORD dst_unused:UNUSED_PAD src0_sel:WORD_1
	v_cvt_pk_f16_f32 v170, v82, v83
	v_cvt_f32_f16_e32 v86, v170
	v_cvt_f32_f16_sdwa v87, v170 dst_sel:DWORD dst_unused:UNUSED_PAD src0_sel:WORD_1
	v_pk_mul_f32 v[172:173], v[88:89], v[88:89]
	v_cvt_f32_f16_e32 v82, v171
	v_add_f32_e32 v139, v172, v139
	v_cvt_f32_f16_sdwa v83, v171 dst_sel:DWORD dst_unused:UNUSED_PAD src0_sel:WORD_1
	v_pk_mul_f32 v[174:175], v[84:85], v[84:85]
	v_add_f32_e32 v139, v173, v139
	v_add_f32_e32 v139, v174, v139
	v_pk_mul_f32 v[196:197], v[86:87], v[86:87]
	v_add_f32_e32 v139, v175, v139
	v_add_f32_e32 v139, v196, v139
	v_pk_mul_f32 v[208:209], v[82:83], v[82:83]
	v_add_f32_e32 v139, v197, v139
	v_add_f32_e32 v139, v208, v139
	v_add_f32_e32 v139, v209, v139
	s_waitcnt lgkmcnt(0)
	v_mov_b32_e32 v149, v139
	s_nop 1
	v_permlane16_swap_b32_e32 v149, v139
	v_lshl_add_u64 v[172:173], s[18:19], 0, v[176:177]
	global_store_dwordx4 v[172:173], v[168:171], off
	s_waitcnt lgkmcnt(0)
	v_add_f32_e32 v139, v139, v149
	v_mov_b32_e32 v149, v139
	s_nop 1
	v_permlane32_swap_b32_e32 v149, v139
	s_and_saveexec_b64 s[28:29], s[4:5]
	s_cbranch_execz .LBB0_573
	s_waitcnt lgkmcnt(0)
	v_add_f32_e32 v139, v139, v149
	v_add_u32_e32 v149, s72, v190
	ds_write_b32 v149, v139 offset:512
; __device__ __forceinline__ float shx(float v, int m, int lane) { return __int_as_float(__builtin_amdgcn_ds_bpermute((lane ^ m) << 2, __float_as_int(v))); }
;     __device__ __forceinline__ void operator()(const f32x4 (&acc)[2][2][4][2], const Unit& u, int wr, int wc, int fr, int fq) const {
;     ...
;         for (int ai = 0; ai < 2; ++ai)
; #pragma unroll
;             for (int m = 0; m < 4; ++m) {
;                 float sq = 0.f;
; #pragma unroll
;                 for (int bj = 0; bj < 2; ++bj) {
;                     const unsigned off = (unsigned)(row0 + ai * HALF + m * 16) * DM + col0 + bj * HALF;
;                     f32x4 xa, xb;
;                     if (F32IN) { xa = *(const f32x4*)(in32 + off); xb = *(const f32x4*)(in32 + off + 4); }
;                     else { const h16x8 xv = *(const h16x8*)(in16 + off); xa = (f32x4){(float)xv[0], (float)xv[1], (float)xv[2], (float)xv[3]}; xb = (f32x4){(float)xv[4], (float)xv[5], (float)xv[6], (float)xv[7]}; }
;                     h16x8 o;
; #pragma unroll
;                     for (int j = 0; j < 4; ++j) { o[j] = (h16)(xa[j] + gv[bj][0][j] * acc[ai][bj][m][0][j]); o[4 + j] = (h16)(xb[j] + gv[bj][1][j] * acc[ai][bj][m][1][j]); }
;                     if (!FINAL) *(h16x8*)(out + off) = o;
;                     ov[ai][m][bj] = o;
; #pragma unroll
;                     for (int j = 0; j < 8; ++j) sq += (float)o[j] * (float)o[j];
;                 }
;                 sq += shx(sq, 16, lane); sq += shx(sq, 32, lane);
;                 if (fq == 0) red[(ai * HALF + wr * 64 + m * 16 + fr) * 4 + wc] = sq;
;             }
.LBB0_573:
	s_or_b64 exec, exec, s[28:29]
	v_add_u32_e32 v168, 0xc000, v32
	v_mov_b32_e32 v169, v33
	s_nop 0
	v_lshlrev_b64 v[172:173], 1, v[168:169]
	v_readlane_b32 s48, v253, 12
	v_readlane_b32 s49, v253, 13
	v_add_u32_e32 v174, 0xc080, v32
	v_mov_b32_e32 v175, v33
	v_lshl_add_u64 v[168:169], s[48:49], 0, v[172:173]
	v_lshlrev_b64 v[176:177], 1, v[174:175]
	v_lshl_add_u64 v[172:173], s[18:19], 0, v[172:173]
	v_lshl_add_u64 v[174:175], s[48:49], 0, v[176:177]
	s_nop 7
	s_nop 4
	s_waitcnt vmcnt(13)
	v_cvt_f32_f16_e32 v196, v242
	v_cvt_f32_f16_sdwa v197, v242 dst_sel:DWORD dst_unused:UNUSED_PAD src0_sel:WORD_1
	v_cvt_f32_f16_e32 v168, v243
	v_cvt_f32_f16_sdwa v169, v243 dst_sel:DWORD dst_unused:UNUSED_PAD src0_sel:WORD_1
	v_cvt_f32_f16_e32 v198, v244
	v_cvt_f32_f16_sdwa v199, v244 dst_sel:DWORD dst_unused:UNUSED_PAD src0_sel:WORD_1
	v_cvt_f32_f16_e32 v170, v245
	v_cvt_f32_f16_sdwa v171, v245 dst_sel:DWORD dst_unused:UNUSED_PAD src0_sel:WORD_1
	v_pk_fma_f32 v[78:79], v[78:79], v[166:167], v[196:197]
	v_pk_fma_f32 v[80:81], v[80:81], v[164:165], v[168:169]
	v_pk_fma_f32 v[74:75], v[74:75], v[162:163], v[198:199]
	v_pk_fma_f32 v[76:77], v[76:77], v[160:161], v[170:171]
	v_cvt_pk_f16_f32 v168, v78, v79
	v_cvt_pk_f16_f32 v169, v80, v81
	v_cvt_pk_f16_f32 v170, v74, v75
	v_cvt_pk_f16_f32 v171, v76, v77
	global_store_dwordx4 v[172:173], v[168:171], off
	v_cvt_f32_f16_e32 v76, v168
	v_cvt_f32_f16_sdwa v77, v168 dst_sel:DWORD dst_unused:UNUSED_PAD src0_sel:WORD_1
	v_cvt_f32_f16_e32 v74, v169
	v_cvt_f32_f16_sdwa v75, v169 dst_sel:DWORD dst_unused:UNUSED_PAD src0_sel:WORD_1
	v_cvt_f32_f16_e32 v80, v170
	v_pk_mul_f32 v[168:169], v[76:77], v[76:77]
	v_cvt_f32_f16_sdwa v81, v170 dst_sel:DWORD dst_unused:UNUSED_PAD src0_sel:WORD_1
	v_cvt_f32_f16_e32 v78, v171
	v_cvt_f32_f16_sdwa v79, v171 dst_sel:DWORD dst_unused:UNUSED_PAD src0_sel:WORD_1
	v_pk_mul_f32 v[170:171], v[74:75], v[74:75]
	v_add_f32_e32 v139, v168, v169
	v_add_f32_e32 v139, v170, v139
	v_add_f32_e32 v139, v171, v139
	v_pk_mul_f32 v[196:197], v[80:81], v[80:81]
	v_pk_mul_f32 v[198:199], v[78:79], v[78:79]
	v_add_f32_e32 v139, v196, v139
	v_add_f32_e32 v139, v197, v139
	v_add_f32_e32 v139, v198, v139
	v_add_f32_e32 v139, v199, v139
	s_waitcnt vmcnt(13)
	v_cvt_f32_f16_e32 v168, v246
	v_cvt_f32_f16_sdwa v169, v246 dst_sel:DWORD dst_unused:UNUSED_PAD src0_sel:WORD_1
	v_cvt_f32_f16_e32 v170, v247
	v_cvt_f32_f16_sdwa v171, v247 dst_sel:DWORD dst_unused:UNUSED_PAD src0_sel:WORD_1
	v_cvt_f32_f16_e32 v172, v248
	v_cvt_f32_f16_sdwa v173, v248 dst_sel:DWORD dst_unused:UNUSED_PAD src0_sel:WORD_1
	v_cvt_f32_f16_e32 v174, v249
	v_cvt_f32_f16_sdwa v175, v249 dst_sel:DWORD dst_unused:UNUSED_PAD src0_sel:WORD_1
	v_readlane_b32 s48, v253, 12
	v_readlane_b32 s49, v253, 13
	s_nop 4
	v_add_u32_e32 v250, 0x58000, v251
	global_load_dwordx4 v[242:245], v250, s[48:49]
	global_load_dwordx4 v[246:249], v250, s[48:49] offset:256
	v_pk_fma_f32 v[70:71], v[70:71], v[158:159], v[168:169]
	v_pk_fma_f32 v[72:73], v[72:73], v[156:157], v[170:171]
	v_cvt_pk_f16_f32 v168, v70, v71
	v_cvt_pk_f16_f32 v169, v72, v73
	v_cvt_f32_f16_e32 v72, v168
	v_cvt_f32_f16_sdwa v73, v168 dst_sel:DWORD dst_unused:UNUSED_PAD src0_sel:WORD_1
	v_pk_fma_f32 v[68:69], v[68:69], v[152:153], v[174:175]
	v_pk_fma_f32 v[66:67], v[66:67], v[154:155], v[172:173]
	v_cvt_pk_f16_f32 v171, v68, v69
	v_cvt_f32_f16_e32 v68, v169
	v_cvt_f32_f16_sdwa v69, v169 dst_sel:DWORD dst_unused:UNUSED_PAD src0_sel:WORD_1
	v_cvt_pk_f16_f32 v170, v66, v67
	v_cvt_f32_f16_e32 v70, v170
	v_cvt_f32_f16_sdwa v71, v170 dst_sel:DWORD dst_unused:UNUSED_PAD src0_sel:WORD_1
	v_pk_mul_f32 v[172:173], v[72:73], v[72:73]
	v_cvt_f32_f16_e32 v66, v171
	v_add_f32_e32 v139, v172, v139
	v_cvt_f32_f16_sdwa v67, v171 dst_sel:DWORD dst_unused:UNUSED_PAD src0_sel:WORD_1
	v_pk_mul_f32 v[174:175], v[68:69], v[68:69]
	v_add_f32_e32 v139, v173, v139
	v_add_f32_e32 v139, v174, v139
	v_pk_mul_f32 v[196:197], v[70:71], v[70:71]
	v_add_f32_e32 v139, v175, v139
	v_add_f32_e32 v139, v196, v139
	v_pk_mul_f32 v[208:209], v[66:67], v[66:67]
	v_add_f32_e32 v139, v197, v139
	v_add_f32_e32 v139, v208, v139
	v_add_f32_e32 v139, v209, v139
	s_waitcnt lgkmcnt(0)
	v_mov_b32_e32 v149, v139
	s_nop 1
	v_permlane16_swap_b32_e32 v149, v139
	v_lshl_add_u64 v[172:173], s[18:19], 0, v[176:177]
	global_store_dwordx4 v[172:173], v[168:171], off
	s_waitcnt lgkmcnt(0)
	v_add_f32_e32 v139, v139, v149
	v_mov_b32_e32 v149, v139
	s_nop 1
	v_permlane32_swap_b32_e32 v149, v139
	s_and_saveexec_b64 s[28:29], s[4:5]
	s_cbranch_execz .LBB0_575
	s_waitcnt lgkmcnt(0)
	v_add_f32_e32 v139, v139, v149
	v_add_u32_e32 v149, s72, v190
	ds_write_b32 v149, v139 offset:768
; __device__ __forceinline__ float shx(float v, int m, int lane) { return __int_as_float(__builtin_amdgcn_ds_bpermute((lane ^ m) << 2, __float_as_int(v))); }
;     __device__ __forceinline__ void operator()(const f32x4 (&acc)[2][2][4][2], const Unit& u, int wr, int wc, int fr, int fq) const {
;     ...
;         for (int ai = 0; ai < 2; ++ai)
; #pragma unroll
;             for (int m = 0; m < 4; ++m) {
;                 float sq = 0.f;
; #pragma unroll
;                 for (int bj = 0; bj < 2; ++bj) {
;                     const unsigned off = (unsigned)(row0 + ai * HALF + m * 16) * DM + col0 + bj * HALF;
;                     f32x4 xa, xb;
;                     if (F32IN) { xa = *(const f32x4*)(in32 + off); xb = *(const f32x4*)(in32 + off + 4); }
;                     else { const h16x8 xv = *(const h16x8*)(in16 + off); xa = (f32x4){(float)xv[0], (float)xv[1], (float)xv[2], (float)xv[3]}; xb = (f32x4){(float)xv[4], (float)xv[5], (float)xv[6], (float)xv[7]}; }
;                     h16x8 o;
; #pragma unroll
;                     for (int j = 0; j < 4; ++j) { o[j] = (h16)(xa[j] + gv[bj][0][j] * acc[ai][bj][m][0][j]); o[4 + j] = (h16)(xb[j] + gv[bj][1][j] * acc[ai][bj][m][1][j]); }
;                     if (!FINAL) *(h16x8*)(out + off) = o;
;                     ov[ai][m][bj] = o;
; #pragma unroll
;                     for (int j = 0; j < 8; ++j) sq += (float)o[j] * (float)o[j];
;                 }
;                 sq += shx(sq, 16, lane); sq += shx(sq, 32, lane);
;                 if (fq == 0) red[(ai * HALF + wr * 64 + m * 16 + fr) * 4 + wc] = sq;
;             }
.LBB0_575:
	s_or_b64 exec, exec, s[28:29]
	v_add_u32_e32 v168, 0x20000, v32
	v_mov_b32_e32 v169, v33
	s_nop 0
	v_lshlrev_b64 v[172:173], 1, v[168:169]
	v_readlane_b32 s48, v253, 12
	v_readlane_b32 s49, v253, 13
	v_add_u32_e32 v174, 0x20080, v32
	v_mov_b32_e32 v175, v33
	v_lshl_add_u64 v[168:169], s[48:49], 0, v[172:173]
	v_lshlrev_b64 v[176:177], 1, v[174:175]
	v_lshl_add_u64 v[172:173], s[18:19], 0, v[172:173]
	v_lshl_add_u64 v[174:175], s[48:49], 0, v[176:177]
	s_nop 7
	s_nop 4
	s_waitcnt vmcnt(14)
	v_cvt_f32_f16_e32 v196, v218
	v_cvt_f32_f16_sdwa v197, v218 dst_sel:DWORD dst_unused:UNUSED_PAD src0_sel:WORD_1
	v_cvt_f32_f16_e32 v168, v219
	v_cvt_f32_f16_sdwa v169, v219 dst_sel:DWORD dst_unused:UNUSED_PAD src0_sel:WORD_1
	v_cvt_f32_f16_e32 v198, v220
	v_cvt_f32_f16_sdwa v199, v220 dst_sel:DWORD dst_unused:UNUSED_PAD src0_sel:WORD_1
	v_cvt_f32_f16_e32 v170, v221
	v_cvt_f32_f16_sdwa v171, v221 dst_sel:DWORD dst_unused:UNUSED_PAD src0_sel:WORD_1
	v_pk_fma_f32 v[62:63], v[62:63], v[166:167], v[196:197]
	v_pk_fma_f32 v[64:65], v[64:65], v[164:165], v[168:169]
	v_pk_fma_f32 v[58:59], v[58:59], v[162:163], v[198:199]
	v_pk_fma_f32 v[60:61], v[60:61], v[160:161], v[170:171]
	v_cvt_pk_f16_f32 v168, v62, v63
	v_cvt_pk_f16_f32 v169, v64, v65
	v_cvt_pk_f16_f32 v170, v58, v59
	v_cvt_pk_f16_f32 v171, v60, v61
	global_store_dwordx4 v[172:173], v[168:171], off
	v_cvt_f32_f16_e32 v60, v168
	v_cvt_f32_f16_sdwa v61, v168 dst_sel:DWORD dst_unused:UNUSED_PAD src0_sel:WORD_1
	v_cvt_f32_f16_e32 v58, v169
	v_cvt_f32_f16_sdwa v59, v169 dst_sel:DWORD dst_unused:UNUSED_PAD src0_sel:WORD_1
	v_cvt_f32_f16_e32 v64, v170
	v_pk_mul_f32 v[168:169], v[60:61], v[60:61]
	v_cvt_f32_f16_sdwa v65, v170 dst_sel:DWORD dst_unused:UNUSED_PAD src0_sel:WORD_1
	v_cvt_f32_f16_e32 v62, v171
	v_cvt_f32_f16_sdwa v63, v171 dst_sel:DWORD dst_unused:UNUSED_PAD src0_sel:WORD_1
	v_pk_mul_f32 v[170:171], v[58:59], v[58:59]
	v_add_f32_e32 v139, v168, v169
	v_add_f32_e32 v139, v170, v139
	v_add_f32_e32 v139, v171, v139
	v_pk_mul_f32 v[196:197], v[64:65], v[64:65]
	v_pk_mul_f32 v[198:199], v[62:63], v[62:63]
	v_add_f32_e32 v139, v196, v139
	v_add_f32_e32 v139, v197, v139
	v_add_f32_e32 v139, v198, v139
	v_add_f32_e32 v139, v199, v139
	s_waitcnt vmcnt(14)
	v_cvt_f32_f16_e32 v168, v222
	v_cvt_f32_f16_sdwa v169, v222 dst_sel:DWORD dst_unused:UNUSED_PAD src0_sel:WORD_1
	v_cvt_f32_f16_e32 v170, v223
	v_cvt_f32_f16_sdwa v171, v223 dst_sel:DWORD dst_unused:UNUSED_PAD src0_sel:WORD_1
	v_cvt_f32_f16_e32 v172, v224
	v_cvt_f32_f16_sdwa v173, v224 dst_sel:DWORD dst_unused:UNUSED_PAD src0_sel:WORD_1
	v_cvt_f32_f16_e32 v174, v225
	v_cvt_f32_f16_sdwa v175, v225 dst_sel:DWORD dst_unused:UNUSED_PAD src0_sel:WORD_1
	v_pk_fma_f32 v[54:55], v[54:55], v[158:159], v[168:169]
	v_pk_fma_f32 v[56:57], v[56:57], v[156:157], v[170:171]
	v_cvt_pk_f16_f32 v168, v54, v55
	v_cvt_pk_f16_f32 v169, v56, v57
	v_cvt_f32_f16_e32 v56, v168
	v_cvt_f32_f16_sdwa v57, v168 dst_sel:DWORD dst_unused:UNUSED_PAD src0_sel:WORD_1
	v_pk_fma_f32 v[52:53], v[52:53], v[152:153], v[174:175]
	v_pk_fma_f32 v[50:51], v[50:51], v[154:155], v[172:173]
	v_cvt_pk_f16_f32 v171, v52, v53
	v_cvt_f32_f16_e32 v52, v169
	v_cvt_f32_f16_sdwa v53, v169 dst_sel:DWORD dst_unused:UNUSED_PAD src0_sel:WORD_1
	v_cvt_pk_f16_f32 v170, v50, v51
	v_cvt_f32_f16_e32 v54, v170
	v_cvt_f32_f16_sdwa v55, v170 dst_sel:DWORD dst_unused:UNUSED_PAD src0_sel:WORD_1
	v_pk_mul_f32 v[172:173], v[56:57], v[56:57]
	v_cvt_f32_f16_e32 v50, v171
	v_add_f32_e32 v139, v172, v139
	v_cvt_f32_f16_sdwa v51, v171 dst_sel:DWORD dst_unused:UNUSED_PAD src0_sel:WORD_1
	v_pk_mul_f32 v[174:175], v[52:53], v[52:53]
	v_add_f32_e32 v139, v173, v139
	v_add_f32_e32 v139, v174, v139
	v_pk_mul_f32 v[196:197], v[54:55], v[54:55]
	v_add_f32_e32 v139, v175, v139
	v_add_f32_e32 v139, v196, v139
	v_pk_mul_f32 v[208:209], v[50:51], v[50:51]
	v_add_f32_e32 v139, v197, v139
	v_add_f32_e32 v139, v208, v139
	v_add_f32_e32 v139, v209, v139
	s_waitcnt lgkmcnt(0)
	v_mov_b32_e32 v149, v139
	s_nop 1
	v_permlane16_swap_b32_e32 v149, v139
	v_lshl_add_u64 v[172:173], s[18:19], 0, v[176:177]
	global_store_dwordx4 v[172:173], v[168:171], off
	s_waitcnt lgkmcnt(0)
	v_add_f32_e32 v139, v139, v149
	v_mov_b32_e32 v149, v139
	s_nop 1
	v_permlane32_swap_b32_e32 v149, v139
	s_and_saveexec_b64 s[28:29], s[4:5]
	s_cbranch_execz .LBB0_577
	s_waitcnt lgkmcnt(0)
	v_add_f32_e32 v139, v139, v149
	v_add_u32_e32 v149, s72, v190
	ds_write_b32 v149, v139 offset:2048
; __device__ __forceinline__ float shx(float v, int m, int lane) { return __int_as_float(__builtin_amdgcn_ds_bpermute((lane ^ m) << 2, __float_as_int(v))); }
;     __device__ __forceinline__ void operator()(const f32x4 (&acc)[2][2][4][2], const Unit& u, int wr, int wc, int fr, int fq) const {
;     ...
;         for (int ai = 0; ai < 2; ++ai)
; #pragma unroll
;             for (int m = 0; m < 4; ++m) {
;                 float sq = 0.f;
; #pragma unroll
;                 for (int bj = 0; bj < 2; ++bj) {
;                     const unsigned off = (unsigned)(row0 + ai * HALF + m * 16) * DM + col0 + bj * HALF;
;                     f32x4 xa, xb;
;                     if (F32IN) { xa = *(const f32x4*)(in32 + off); xb = *(const f32x4*)(in32 + off + 4); }
;                     else { const h16x8 xv = *(const h16x8*)(in16 + off); xa = (f32x4){(float)xv[0], (float)xv[1], (float)xv[2], (float)xv[3]}; xb = (f32x4){(float)xv[4], (float)xv[5], (float)xv[6], (float)xv[7]}; }
;                     h16x8 o;
; #pragma unroll
;                     for (int j = 0; j < 4; ++j) { o[j] = (h16)(xa[j] + gv[bj][0][j] * acc[ai][bj][m][0][j]); o[4 + j] = (h16)(xb[j] + gv[bj][1][j] * acc[ai][bj][m][1][j]); }
;                     if (!FINAL) *(h16x8*)(out + off) = o;
;                     ov[ai][m][bj] = o;
; #pragma unroll
;                     for (int j = 0; j < 8; ++j) sq += (float)o[j] * (float)o[j];
;                 }
;                 sq += shx(sq, 16, lane); sq += shx(sq, 32, lane);
;                 if (fq == 0) red[(ai * HALF + wr * 64 + m * 16 + fr) * 4 + wc] = sq;
;             }
.LBB0_577:
	s_or_b64 exec, exec, s[28:29]
	v_add_u32_e32 v168, 0x24000, v32
	v_mov_b32_e32 v169, v33
	s_nop 0
	v_lshlrev_b64 v[172:173], 1, v[168:169]
	v_readlane_b32 s48, v253, 12
	v_readlane_b32 s49, v253, 13
	v_add_u32_e32 v174, 0x24080, v32
	v_mov_b32_e32 v175, v33
	v_lshl_add_u64 v[168:169], s[48:49], 0, v[172:173]
	v_lshlrev_b64 v[176:177], 1, v[174:175]
	v_lshl_add_u64 v[172:173], s[18:19], 0, v[172:173]
	v_lshl_add_u64 v[174:175], s[48:49], 0, v[176:177]
	s_nop 7
	s_nop 4
	s_waitcnt vmcnt(12)
	v_cvt_f32_f16_e32 v196, v226
	v_cvt_f32_f16_sdwa v197, v226 dst_sel:DWORD dst_unused:UNUSED_PAD src0_sel:WORD_1
	v_cvt_f32_f16_e32 v168, v227
	v_cvt_f32_f16_sdwa v169, v227 dst_sel:DWORD dst_unused:UNUSED_PAD src0_sel:WORD_1
	v_cvt_f32_f16_e32 v198, v228
	v_cvt_f32_f16_sdwa v199, v228 dst_sel:DWORD dst_unused:UNUSED_PAD src0_sel:WORD_1
	v_cvt_f32_f16_e32 v170, v229
	v_cvt_f32_f16_sdwa v171, v229 dst_sel:DWORD dst_unused:UNUSED_PAD src0_sel:WORD_1
	v_pk_fma_f32 v[46:47], v[46:47], v[166:167], v[196:197]
	v_pk_fma_f32 v[48:49], v[48:49], v[164:165], v[168:169]
	v_pk_fma_f32 v[42:43], v[42:43], v[162:163], v[198:199]
	v_pk_fma_f32 v[44:45], v[44:45], v[160:161], v[170:171]
	v_cvt_pk_f16_f32 v168, v46, v47
	v_cvt_pk_f16_f32 v169, v48, v49
	v_cvt_pk_f16_f32 v170, v42, v43
	v_cvt_pk_f16_f32 v171, v44, v45
	global_store_dwordx4 v[172:173], v[168:171], off
	v_cvt_f32_f16_e32 v48, v168
	v_cvt_f32_f16_sdwa v49, v168 dst_sel:DWORD dst_unused:UNUSED_PAD src0_sel:WORD_1
	v_cvt_f32_f16_e32 v44, v169
	v_cvt_f32_f16_sdwa v45, v169 dst_sel:DWORD dst_unused:UNUSED_PAD src0_sel:WORD_1
	v_cvt_f32_f16_e32 v46, v170
	v_pk_mul_f32 v[168:169], v[48:49], v[48:49]
	v_cvt_f32_f16_sdwa v47, v170 dst_sel:DWORD dst_unused:UNUSED_PAD src0_sel:WORD_1
	v_cvt_f32_f16_e32 v42, v171
	v_cvt_f32_f16_sdwa v43, v171 dst_sel:DWORD dst_unused:UNUSED_PAD src0_sel:WORD_1
	v_pk_mul_f32 v[170:171], v[44:45], v[44:45]
	v_add_f32_e32 v139, v168, v169
	v_add_f32_e32 v139, v170, v139
	v_add_f32_e32 v139, v171, v139
	v_pk_mul_f32 v[196:197], v[46:47], v[46:47]
	v_pk_mul_f32 v[198:199], v[42:43], v[42:43]
	v_add_f32_e32 v139, v196, v139
	v_add_f32_e32 v139, v197, v139
	v_add_f32_e32 v139, v198, v139
	v_add_f32_e32 v139, v199, v139
	s_waitcnt vmcnt(12)
	v_cvt_f32_f16_e32 v168, v230
	v_cvt_f32_f16_sdwa v169, v230 dst_sel:DWORD dst_unused:UNUSED_PAD src0_sel:WORD_1
	v_cvt_f32_f16_e32 v170, v231
	v_cvt_f32_f16_sdwa v171, v231 dst_sel:DWORD dst_unused:UNUSED_PAD src0_sel:WORD_1
	v_cvt_f32_f16_e32 v172, v232
	v_cvt_f32_f16_sdwa v173, v232 dst_sel:DWORD dst_unused:UNUSED_PAD src0_sel:WORD_1
	v_cvt_f32_f16_e32 v174, v233
	v_cvt_f32_f16_sdwa v175, v233 dst_sel:DWORD dst_unused:UNUSED_PAD src0_sel:WORD_1
	v_pk_fma_f32 v[38:39], v[38:39], v[158:159], v[168:169]
	v_pk_fma_f32 v[40:41], v[40:41], v[156:157], v[170:171]
	v_cvt_pk_f16_f32 v168, v38, v39
	v_cvt_pk_f16_f32 v169, v40, v41
	v_cvt_f32_f16_e32 v40, v168
	v_cvt_f32_f16_sdwa v41, v168 dst_sel:DWORD dst_unused:UNUSED_PAD src0_sel:WORD_1
	v_pk_fma_f32 v[36:37], v[36:37], v[152:153], v[174:175]
	v_pk_fma_f32 v[34:35], v[34:35], v[154:155], v[172:173]
	v_cvt_pk_f16_f32 v171, v36, v37
	v_cvt_f32_f16_e32 v36, v169
	v_cvt_f32_f16_sdwa v37, v169 dst_sel:DWORD dst_unused:UNUSED_PAD src0_sel:WORD_1
	v_cvt_pk_f16_f32 v170, v34, v35
	v_cvt_f32_f16_e32 v38, v170
	v_cvt_f32_f16_sdwa v39, v170 dst_sel:DWORD dst_unused:UNUSED_PAD src0_sel:WORD_1
	v_pk_mul_f32 v[172:173], v[40:41], v[40:41]
	v_cvt_f32_f16_e32 v34, v171
	v_add_f32_e32 v139, v172, v139
	v_cvt_f32_f16_sdwa v35, v171 dst_sel:DWORD dst_unused:UNUSED_PAD src0_sel:WORD_1
	v_pk_mul_f32 v[174:175], v[36:37], v[36:37]
	v_add_f32_e32 v139, v173, v139
	v_add_f32_e32 v139, v174, v139
	v_pk_mul_f32 v[196:197], v[38:39], v[38:39]
	v_add_f32_e32 v139, v175, v139
	v_add_f32_e32 v139, v196, v139
	v_pk_mul_f32 v[208:209], v[34:35], v[34:35]
	v_add_f32_e32 v139, v197, v139
	v_add_f32_e32 v139, v208, v139
	v_add_f32_e32 v139, v209, v139
	s_waitcnt lgkmcnt(0)
	v_mov_b32_e32 v149, v139
	s_nop 1
	v_permlane16_swap_b32_e32 v149, v139
	v_lshl_add_u64 v[172:173], s[18:19], 0, v[176:177]
	global_store_dwordx4 v[172:173], v[168:171], off
	s_waitcnt lgkmcnt(0)
	v_add_f32_e32 v139, v139, v149
	v_mov_b32_e32 v149, v139
	s_nop 1
	v_permlane32_swap_b32_e32 v149, v139
	s_and_saveexec_b64 s[28:29], s[4:5]
	s_cbranch_execz .LBB0_579
	s_waitcnt lgkmcnt(0)
	v_add_f32_e32 v139, v139, v149
	v_add_u32_e32 v149, s72, v190
	ds_write_b32 v149, v139 offset:2304
; __device__ __forceinline__ float shx(float v, int m, int lane) { return __int_as_float(__builtin_amdgcn_ds_bpermute((lane ^ m) << 2, __float_as_int(v))); }
;     __device__ __forceinline__ void operator()(const f32x4 (&acc)[2][2][4][2], const Unit& u, int wr, int wc, int fr, int fq) const {
;     ...
;         for (int ai = 0; ai < 2; ++ai)
; #pragma unroll
;             for (int m = 0; m < 4; ++m) {
;                 float sq = 0.f;
; #pragma unroll
;                 for (int bj = 0; bj < 2; ++bj) {
;                     const unsigned off = (unsigned)(row0 + ai * HALF + m * 16) * DM + col0 + bj * HALF;
;                     f32x4 xa, xb;
;                     if (F32IN) { xa = *(const f32x4*)(in32 + off); xb = *(const f32x4*)(in32 + off + 4); }
;                     else { const h16x8 xv = *(const h16x8*)(in16 + off); xa = (f32x4){(float)xv[0], (float)xv[1], (float)xv[2], (float)xv[3]}; xb = (f32x4){(float)xv[4], (float)xv[5], (float)xv[6], (float)xv[7]}; }
;                     h16x8 o;
; #pragma unroll
;                     for (int j = 0; j < 4; ++j) { o[j] = (h16)(xa[j] + gv[bj][0][j] * acc[ai][bj][m][0][j]); o[4 + j] = (h16)(xb[j] + gv[bj][1][j] * acc[ai][bj][m][1][j]); }
;                     if (!FINAL) *(h16x8*)(out + off) = o;
;                     ov[ai][m][bj] = o;
; #pragma unroll
;                     for (int j = 0; j < 8; ++j) sq += (float)o[j] * (float)o[j];
;                 }
;                 sq += shx(sq, 16, lane); sq += shx(sq, 32, lane);
;                 if (fq == 0) red[(ai * HALF + wr * 64 + m * 16 + fr) * 4 + wc] = sq;
;             }
.LBB0_579:
	s_or_b64 exec, exec, s[28:29]
	v_add_u32_e32 v168, 0x28000, v32
	v_mov_b32_e32 v169, v33
	s_nop 0
	v_lshlrev_b64 v[172:173], 1, v[168:169]
	v_readlane_b32 s48, v253, 12
	v_readlane_b32 s49, v253, 13
	v_add_u32_e32 v174, 0x28080, v32
	v_mov_b32_e32 v175, v33
	v_lshl_add_u64 v[168:169], s[48:49], 0, v[172:173]
	v_lshlrev_b64 v[176:177], 1, v[174:175]
	v_lshl_add_u64 v[172:173], s[18:19], 0, v[172:173]
	v_lshl_add_u64 v[174:175], s[48:49], 0, v[176:177]
	s_nop 7
	s_nop 4
	s_waitcnt vmcnt(10)
	v_cvt_f32_f16_e32 v196, v234
	v_cvt_f32_f16_sdwa v197, v234 dst_sel:DWORD dst_unused:UNUSED_PAD src0_sel:WORD_1
	v_cvt_f32_f16_e32 v168, v235
	v_cvt_f32_f16_sdwa v169, v235 dst_sel:DWORD dst_unused:UNUSED_PAD src0_sel:WORD_1
	v_cvt_f32_f16_e32 v198, v236
	v_cvt_f32_f16_sdwa v199, v236 dst_sel:DWORD dst_unused:UNUSED_PAD src0_sel:WORD_1
	v_cvt_f32_f16_e32 v170, v237
	v_cvt_f32_f16_sdwa v171, v237 dst_sel:DWORD dst_unused:UNUSED_PAD src0_sel:WORD_1
	v_pk_fma_f32 v[28:29], v[28:29], v[166:167], v[196:197]
	v_pk_fma_f32 v[30:31], v[30:31], v[164:165], v[168:169]
	v_pk_fma_f32 v[24:25], v[24:25], v[162:163], v[198:199]
	v_pk_fma_f32 v[26:27], v[26:27], v[160:161], v[170:171]
	v_cvt_pk_f16_f32 v168, v28, v29
	v_cvt_pk_f16_f32 v169, v30, v31
	v_cvt_pk_f16_f32 v170, v24, v25
	v_cvt_pk_f16_f32 v171, v26, v27
	global_store_dwordx4 v[172:173], v[168:171], off
	v_cvt_f32_f16_e32 v30, v168
	v_cvt_f32_f16_sdwa v31, v168 dst_sel:DWORD dst_unused:UNUSED_PAD src0_sel:WORD_1
	v_cvt_f32_f16_e32 v26, v169
	v_cvt_f32_f16_sdwa v27, v169 dst_sel:DWORD dst_unused:UNUSED_PAD src0_sel:WORD_1
	v_cvt_f32_f16_e32 v28, v170
	v_pk_mul_f32 v[168:169], v[30:31], v[30:31]
	v_cvt_f32_f16_sdwa v29, v170 dst_sel:DWORD dst_unused:UNUSED_PAD src0_sel:WORD_1
	v_cvt_f32_f16_e32 v24, v171
	v_cvt_f32_f16_sdwa v25, v171 dst_sel:DWORD dst_unused:UNUSED_PAD src0_sel:WORD_1
	v_pk_mul_f32 v[170:171], v[26:27], v[26:27]
	v_add_f32_e32 v139, v168, v169
	v_add_f32_e32 v139, v170, v139
	v_add_f32_e32 v139, v171, v139
	v_pk_mul_f32 v[196:197], v[28:29], v[28:29]
	v_pk_mul_f32 v[198:199], v[24:25], v[24:25]
	v_add_f32_e32 v139, v196, v139
	v_add_f32_e32 v139, v197, v139
	v_add_f32_e32 v139, v198, v139
	v_add_f32_e32 v139, v199, v139
	s_waitcnt vmcnt(10)
	v_cvt_f32_f16_e32 v168, v238
	v_cvt_f32_f16_sdwa v169, v238 dst_sel:DWORD dst_unused:UNUSED_PAD src0_sel:WORD_1
	v_cvt_f32_f16_e32 v170, v239
	v_cvt_f32_f16_sdwa v171, v239 dst_sel:DWORD dst_unused:UNUSED_PAD src0_sel:WORD_1
	v_cvt_f32_f16_e32 v172, v240
	v_cvt_f32_f16_sdwa v173, v240 dst_sel:DWORD dst_unused:UNUSED_PAD src0_sel:WORD_1
	v_cvt_f32_f16_e32 v174, v241
	v_cvt_f32_f16_sdwa v175, v241 dst_sel:DWORD dst_unused:UNUSED_PAD src0_sel:WORD_1
	v_pk_fma_f32 v[20:21], v[20:21], v[158:159], v[168:169]
	v_pk_fma_f32 v[22:23], v[22:23], v[156:157], v[170:171]
	v_cvt_pk_f16_f32 v168, v20, v21
	v_cvt_pk_f16_f32 v169, v22, v23
	v_cvt_f32_f16_e32 v22, v168
	v_cvt_f32_f16_sdwa v23, v168 dst_sel:DWORD dst_unused:UNUSED_PAD src0_sel:WORD_1
	v_pk_fma_f32 v[18:19], v[18:19], v[152:153], v[174:175]
	v_pk_fma_f32 v[16:17], v[16:17], v[154:155], v[172:173]
	v_cvt_pk_f16_f32 v171, v18, v19
	v_cvt_f32_f16_e32 v18, v169
	v_cvt_f32_f16_sdwa v19, v169 dst_sel:DWORD dst_unused:UNUSED_PAD src0_sel:WORD_1
	v_cvt_pk_f16_f32 v170, v16, v17
	v_cvt_f32_f16_e32 v20, v170
	v_cvt_f32_f16_sdwa v21, v170 dst_sel:DWORD dst_unused:UNUSED_PAD src0_sel:WORD_1
	v_pk_mul_f32 v[172:173], v[22:23], v[22:23]
	v_cvt_f32_f16_e32 v16, v171
	v_add_f32_e32 v139, v172, v139
	v_cvt_f32_f16_sdwa v17, v171 dst_sel:DWORD dst_unused:UNUSED_PAD src0_sel:WORD_1
	v_pk_mul_f32 v[174:175], v[18:19], v[18:19]
	v_add_f32_e32 v139, v173, v139
	v_add_f32_e32 v139, v174, v139
	v_pk_mul_f32 v[196:197], v[20:21], v[20:21]
	v_add_f32_e32 v139, v175, v139
	v_add_f32_e32 v139, v196, v139
	v_pk_mul_f32 v[208:209], v[16:17], v[16:17]
	v_add_f32_e32 v139, v197, v139
	v_add_f32_e32 v139, v208, v139
	v_add_f32_e32 v139, v209, v139
	s_waitcnt lgkmcnt(0)
	v_mov_b32_e32 v149, v139
	s_nop 1
	v_permlane16_swap_b32_e32 v149, v139
	v_lshl_add_u64 v[172:173], s[18:19], 0, v[176:177]
	global_store_dwordx4 v[172:173], v[168:171], off
	s_waitcnt lgkmcnt(0)
	v_add_f32_e32 v139, v139, v149
	v_mov_b32_e32 v149, v139
	s_nop 1
	v_permlane32_swap_b32_e32 v149, v139
	s_and_saveexec_b64 s[28:29], s[4:5]
	s_cbranch_execz .LBB0_581
	s_waitcnt lgkmcnt(0)
	v_add_f32_e32 v139, v139, v149
	v_add_u32_e32 v149, s72, v190
	ds_write_b32 v149, v139 offset:2560
; __device__ __forceinline__ float shx(float v, int m, int lane) { return __int_as_float(__builtin_amdgcn_ds_bpermute((lane ^ m) << 2, __float_as_int(v))); }
;     __device__ __forceinline__ void operator()(const f32x4 (&acc)[2][2][4][2], const Unit& u, int wr, int wc, int fr, int fq) const {
;     ...
;         for (int ai = 0; ai < 2; ++ai)
; #pragma unroll
;             for (int m = 0; m < 4; ++m) {
;                 float sq = 0.f;
; #pragma unroll
;                 for (int bj = 0; bj < 2; ++bj) {
;                     const unsigned off = (unsigned)(row0 + ai * HALF + m * 16) * DM + col0 + bj * HALF;
;                     f32x4 xa, xb;
;                     if (F32IN) { xa = *(const f32x4*)(in32 + off); xb = *(const f32x4*)(in32 + off + 4); }
;                     else { const h16x8 xv = *(const h16x8*)(in16 + off); xa = (f32x4){(float)xv[0], (float)xv[1], (float)xv[2], (float)xv[3]}; xb = (f32x4){(float)xv[4], (float)xv[5], (float)xv[6], (float)xv[7]}; }
;                     h16x8 o;
; #pragma unroll
;                     for (int j = 0; j < 4; ++j) { o[j] = (h16)(xa[j] + gv[bj][0][j] * acc[ai][bj][m][0][j]); o[4 + j] = (h16)(xb[j] + gv[bj][1][j] * acc[ai][bj][m][1][j]); }
;                     if (!FINAL) *(h16x8*)(out + off) = o;
;                     ov[ai][m][bj] = o;
; #pragma unroll
;                     for (int j = 0; j < 8; ++j) sq += (float)o[j] * (float)o[j];
;                 }
;                 sq += shx(sq, 16, lane); sq += shx(sq, 32, lane);
;                 if (fq == 0) red[(ai * HALF + wr * 64 + m * 16 + fr) * 4 + wc] = sq;
;             }
.LBB0_581:
	s_or_b64 exec, exec, s[28:29]
	v_add_u32_e32 v168, 0x2c000, v32
	v_mov_b32_e32 v169, v33
	s_nop 0
	v_lshlrev_b64 v[172:173], 1, v[168:169]
	v_readlane_b32 s48, v253, 12
	v_readlane_b32 s49, v253, 13
	v_lshl_add_u64 v[176:177], s[18:19], 0, v[172:173]
	v_add_u32_e32 v32, 0x2c080, v32
	v_lshl_add_u64 v[168:169], s[48:49], 0, v[172:173]
	s_nop 5
	v_readlane_b32 s43, v253, 7
	v_readlane_b32 s44, v253, 8
	s_nop 0
	v_readlane_b32 s46, v253, 10
	s_nop 2
	s_waitcnt vmcnt(8)
	v_cvt_f32_f16_e32 v172, v242
	v_cvt_f32_f16_sdwa v173, v242 dst_sel:DWORD dst_unused:UNUSED_PAD src0_sel:WORD_1
	v_cvt_f32_f16_e32 v168, v243
	v_cvt_f32_f16_sdwa v169, v243 dst_sel:DWORD dst_unused:UNUSED_PAD src0_sel:WORD_1
	v_pk_fma_f32 v[12:13], v[12:13], v[166:167], v[172:173]
	s_nop 0
	v_cvt_pk_f16_f32 v172, v12, v13
	v_pk_fma_f32 v[14:15], v[14:15], v[164:165], v[168:169]
	v_cvt_f32_f16_e32 v168, v244
	v_cvt_f32_f16_sdwa v169, v244 dst_sel:DWORD dst_unused:UNUSED_PAD src0_sel:WORD_1
	v_cvt_pk_f16_f32 v173, v14, v15
	v_cvt_f32_f16_e32 v166, v172
	v_cvt_f32_f16_sdwa v167, v172 dst_sel:DWORD dst_unused:UNUSED_PAD src0_sel:WORD_1
	v_pk_fma_f32 v[8:9], v[8:9], v[162:163], v[168:169]
	v_cvt_f32_f16_e32 v164, v173
	v_cvt_pk_f16_f32 v174, v8, v9
	v_cvt_f32_f16_e32 v8, v245
	v_cvt_f32_f16_sdwa v9, v245 dst_sel:DWORD dst_unused:UNUSED_PAD src0_sel:WORD_1
	v_cvt_f32_f16_sdwa v165, v173 dst_sel:DWORD dst_unused:UNUSED_PAD src0_sel:WORD_1
	v_cvt_f32_f16_e32 v162, v174
	v_cvt_f32_f16_sdwa v163, v174 dst_sel:DWORD dst_unused:UNUSED_PAD src0_sel:WORD_1
	v_pk_fma_f32 v[8:9], v[10:11], v[160:161], v[8:9]
	v_lshlrev_b64 v[10:11], 1, v[32:33]
	v_cvt_pk_f16_f32 v175, v8, v9
	global_store_dwordx4 v[176:177], v[172:175], off
	v_lshl_add_u64 v[170:171], s[48:49], 0, v[10:11]
	v_cvt_f32_f16_e32 v160, v175
	v_cvt_f32_f16_sdwa v161, v175 dst_sel:DWORD dst_unused:UNUSED_PAD src0_sel:WORD_1
	v_pk_mul_f32 v[12:13], v[166:167], v[166:167]
	v_lshl_add_u64 v[10:11], s[18:19], 0, v[10:11]
	v_pk_mul_f32 v[14:15], v[164:165], v[164:165]
	v_pk_mul_f32 v[168:169], v[162:163], v[162:163]
	v_pk_mul_f32 v[8:9], v[160:161], v[160:161]
	s_waitcnt vmcnt(8)
	v_cvt_f32_f16_e32 v174, v246
	v_cvt_f32_f16_sdwa v175, v246 dst_sel:DWORD dst_unused:UNUSED_PAD src0_sel:WORD_1
	v_pk_fma_f32 v[4:5], v[4:5], v[158:159], v[174:175]
	v_cvt_f32_f16_e32 v174, v247
	v_cvt_f32_f16_sdwa v175, v247 dst_sel:DWORD dst_unused:UNUSED_PAD src0_sel:WORD_1
	v_cvt_pk_f16_f32 v170, v4, v5
	v_cvt_f32_f16_e32 v158, v170
	v_cvt_f32_f16_sdwa v159, v170 dst_sel:DWORD dst_unused:UNUSED_PAD src0_sel:WORD_1
	v_pk_fma_f32 v[6:7], v[6:7], v[156:157], v[174:175]
	v_cvt_f32_f16_e32 v174, v248
	v_cvt_f32_f16_sdwa v175, v248 dst_sel:DWORD dst_unused:UNUSED_PAD src0_sel:WORD_1
	v_cvt_pk_f16_f32 v171, v6, v7
	v_cvt_f32_f16_e32 v156, v171
	v_cvt_f32_f16_sdwa v157, v171 dst_sel:DWORD dst_unused:UNUSED_PAD src0_sel:WORD_1
	v_pk_fma_f32 v[0:1], v[0:1], v[154:155], v[174:175]
	v_cvt_f32_f16_e32 v174, v249
	v_cvt_f32_f16_sdwa v175, v249 dst_sel:DWORD dst_unused:UNUSED_PAD src0_sel:WORD_1
	v_cvt_pk_f16_f32 v172, v0, v1
	v_pk_mul_f32 v[4:5], v[158:159], v[158:159]
	v_cvt_f32_f16_e32 v154, v172
	v_pk_fma_f32 v[2:3], v[2:3], v[152:153], v[174:175]
	v_cvt_f32_f16_sdwa v155, v172 dst_sel:DWORD dst_unused:UNUSED_PAD src0_sel:WORD_1
	v_cvt_pk_f16_f32 v173, v2, v3
	global_store_dwordx4 v[10:11], v[170:173], off
	v_add_f32_e32 v10, v12, v13
	v_add_f32_e32 v10, v14, v10
	v_add_f32_e32 v10, v15, v10
	v_add_f32_e32 v10, v168, v10
	v_add_f32_e32 v10, v169, v10
	v_add_f32_e32 v8, v8, v10
	v_add_f32_e32 v8, v9, v8
	v_add_f32_e32 v4, v4, v8
	v_pk_mul_f32 v[6:7], v[156:157], v[156:157]
	v_cvt_f32_f16_e32 v152, v173
	v_cvt_f32_f16_sdwa v153, v173 dst_sel:DWORD dst_unused:UNUSED_PAD src0_sel:WORD_1
	v_add_f32_e32 v4, v5, v4
	v_add_f32_e32 v4, v6, v4
	v_pk_mul_f32 v[0:1], v[154:155], v[154:155]
	v_add_f32_e32 v4, v7, v4
	v_add_f32_e32 v0, v0, v4
	v_pk_mul_f32 v[2:3], v[152:153], v[152:153]
	v_add_f32_e32 v0, v1, v0
	v_add_f32_e32 v0, v2, v0
	v_add_f32_e32 v0, v3, v0
	v_mov_b32_e32 v1, v0
	s_nop 1
	v_permlane16_swap_b32_e32 v1, v0
	s_waitcnt lgkmcnt(0)
	v_add_f32_e32 v0, v0, v1
	v_mov_b32_e32 v1, v0
	s_nop 1
	v_permlane32_swap_b32_e32 v1, v0
	s_and_saveexec_b64 s[28:29], s[4:5]
	s_cbranch_execz .LBB0_583
	s_waitcnt lgkmcnt(0)
	v_add_f32_e32 v0, v0, v1
	v_add_u32_e32 v1, s72, v190
	ds_write_b32 v1, v0 offset:2816
